# B window loop back edge rotated: loop-carried state copies and exit test moved in front of the per-tile barrier (exit path has its own barrier copy)
# speedup vs baseline: 1.0056x; 1.0010x over previous
.LBB0_611:
	s_xor_b32 s55, s55, 1
	s_add_i32 s45, s45, 1
	s_add_i32 s92, s92, 64
	s_andn2_b64 vcc, exec, s[38:39]
	v_subrev_u32_e32 v120, 64, v120
	s_cbranch_vccz .Lwinrot_exit
	v_mov_b32_e32 v136, v131
	v_mov_b32_e32 v124, v151
	s_nop 7
	s_nop 3
	v_mov_b32_e32 v144, v80
	v_mov_b32_e32 v145, v81
	v_mov_b32_e32 v146, v82
	v_mov_b32_e32 v147, v83
	v_mov_b32_e32 v140, v92
	v_mov_b32_e32 v141, v93
	v_mov_b32_e32 v142, v94
	v_mov_b32_e32 v143, v95
	v_mov_b32_e32 v134, v104
	v_mov_b32_e32 v135, v105
	v_mov_b32_e32 v138, v106
	v_mov_b32_e32 v139, v107
	v_mov_b32_e32 v128, v108
	v_mov_b32_e32 v129, v109
	v_mov_b32_e32 v132, v110
	v_mov_b32_e32 v133, v111
	s_waitcnt lgkmcnt(0)
	s_barrier
	s_branch .LBB0_605
.Lwinrot_exit:
	s_waitcnt lgkmcnt(0)
	s_barrier
	s_branch .LBB0_384
